# loop-edge rotation (7.11) on the FFN-up K-loop: counter/address SALU block issued in the last MFMA block, only the branch after the loop-back barrier
# speedup vs baseline: 1.0161x; 1.0161x over previous
; #define PG8_STAGE(bufoff, gbase, voff) do { _Pragma("unroll") for (int _i = 0; _i < 2; ++_i) \
;         __builtin_amdgcn_global_load_lds((const unsigned*)((const char*)(gbase) + (voff)[_i]), (LAS unsigned*)(lds + (bufoff) + ldsw + _i * 8192), 16, 0, 0); } while (0)
; #define PG8_LDA(dst, b, h) do { _Pragma("unroll") for (int m = 0; m < 4; ++m) _Pragma("unroll") for (int k = 0; k < 2; ++k) dst[m][k] = *(const LAS bf16x8*)(lds + PG8_SA(b, h) + aoff + m * 2048 + k * 1024); } while (0)
; #define PG8_LDB(dst, b, h) do { _Pragma("unroll") for (int n = 0; n < 2; ++n) _Pragma("unroll") for (int k = 0; k < 2; ++k) dst[n][k] = *(const LAS bf16x8*)(lds + PG8_SB(b, h) + boff + n * 2048 + k * 1024); } while (0)
; #define PG8_MMA(ai, bj, At, Bt) do { __builtin_amdgcn_s_setprio(1); _Pragma("unroll") for (int m = 0; m < 4; ++m) _Pragma("unroll") for (int n = 0; n < 2; ++n) _Pragma("unroll") for (int k = 0; k < 2; ++k) \
;         acc[ai][bj][m][n] = __builtin_amdgcn_mfma_f32_16x16x32_bf16(Bt[n][k], At[m][k], acc[ai][bj][m][n], 0, 0, 0); __builtin_amdgcn_s_setprio(0); } while (0)
; #define PG8_WAIT_V(n) asm volatile("s_waitcnt vmcnt(" #n ")" ::: "memory")
; #define PG8_WAIT_L(n) asm volatile("s_waitcnt lgkmcnt(" #n ")" ::: "memory")
; #define PG8_BAR __builtin_amdgcn_s_barrier()
; #define PG8_SCHED __builtin_amdgcn_sched_barrier(0)
; template <class Epi, bool ALIGN_EPI, bool SP2, bool ROWHALF = false>
; DI void gemm_phase(LAS unsigned char* lds, const Gemm g, const StaticOrder& S, const Epi& E) {
;     ...
;             if constexpr (SP2) {
;             PG8_LDB(B0, 0, 0); PG8_LDB(B1, 0, 1); PG8_SCHED; PG8_LDA(At, 0, 0); PG8_STAGE(PG8_SA(1, 1), a1 + hA1, voffA);
;             PG8_WAIT_V(8); PG8_WAIT_L(0); PG8_BAR; PG8_MMA(0, 0, At, B0); PG8_MMA(0, 1, At, B1); PG8_BAR; PG8_SCHED;
;             if constexpr (!ROWHALF) { PG8_LDA(At, 0, 1); } PG8_STAGE(PG8_SB(0, 0), b2, voffB); PG8_STAGE(PG8_SB(0, 1), b2 + hstepB, voffB); PG8_STAGE(PG8_SA(0, 0), a2 + hA0, voffA);
;             PG8_WAIT_V(8); PG8_WAIT_L(0); PG8_BAR; if constexpr (!ROWHALF) { PG8_MMA(1, 0, At, B0); PG8_MMA(1, 1, At, B1); } PG8_BAR; PG8_SCHED;
.Lk240_body:
	v_add_u32_e32 v156, s54, v145
	v_add_u32_e32 v160, s55, v145
	ds_read_b128 v[140:143], v156
	ds_read_b128 v[148:151], v156 offset:1024
	ds_read_b128 v[152:155], v156 offset:2048
	ds_read_b128 v[156:159], v156 offset:3072
	ds_read_b128 v[164:167], v160
	ds_read_b128 v[168:171], v160 offset:1024
	ds_read_b128 v[172:175], v160 offset:2048
	ds_read_b128 v[176:179], v160 offset:3072
	v_lshl_add_u64 v[160:161], s[74:75], 0, v[136:137]
	s_add_i32 m0, s9, 0xc000
	ds_read_b128 v[180:183], v147
	ds_read_b128 v[184:187], v147 offset:1024
	ds_read_b128 v[216:219], v147 offset:2048
	ds_read_b128 v[220:223], v147 offset:3072
	ds_read_b128 v[224:227], v147 offset:4096
	ds_read_b128 v[228:231], v147 offset:5120
	ds_read_b128 v[232:235], v147 offset:6144
	ds_read_b128 v[236:239], v147 offset:7168
	global_load_lds_dwordx4 v[160:161], off
	v_lshl_add_u64 v[160:161], s[74:75], 0, v[138:139]
	s_add_i32 m0, s9, 0xe000
	s_nop 0
	global_load_lds_dwordx4 v[160:161], off
	s_waitcnt vmcnt(8)
	s_waitcnt lgkmcnt(0)
	s_setprio 1
	v_mfma_f32_16x16x32_bf16 v[126:129], v[140:143], v[180:183], v[126:129]
	v_mfma_f32_16x16x32_bf16 v[118:121], v[152:155], v[180:183], v[118:121]
	v_mfma_f32_16x16x32_bf16 v[110:113], v[140:143], v[216:219], v[110:113]
	v_mfma_f32_16x16x32_bf16 v[102:105], v[152:155], v[216:219], v[102:105]
	s_barrier
	v_mfma_f32_16x16x32_bf16 v[92:95], v[140:143], v[224:227], v[92:95]
	v_mfma_f32_16x16x32_bf16 v[84:87], v[152:155], v[224:227], v[84:87]
	v_mfma_f32_16x16x32_bf16 v[76:79], v[140:143], v[232:235], v[76:79]
	v_mfma_f32_16x16x32_bf16 v[68:71], v[152:155], v[232:235], v[68:71]
	v_mfma_f32_16x16x32_bf16 v[126:129], v[148:151], v[184:187], v[126:129]
	v_mfma_f32_16x16x32_bf16 v[118:121], v[156:159], v[184:187], v[118:121]
	v_mfma_f32_16x16x32_bf16 v[110:113], v[148:151], v[220:223], v[110:113]
	v_mfma_f32_16x16x32_bf16 v[102:105], v[156:159], v[220:223], v[102:105]
	v_mfma_f32_16x16x32_bf16 v[92:95], v[148:151], v[228:231], v[92:95]
	v_mfma_f32_16x16x32_bf16 v[84:87], v[156:159], v[228:231], v[84:87]
	v_mfma_f32_16x16x32_bf16 v[76:79], v[148:151], v[236:239], v[76:79]
	v_mfma_f32_16x16x32_bf16 v[68:71], v[156:159], v[236:239], v[68:71]
	s_setprio 0
	s_setprio 1
	v_mfma_f32_16x16x32_bf16 v[122:125], v[164:167], v[180:183], v[122:125]
	v_mfma_f32_16x16x32_bf16 v[114:117], v[172:175], v[180:183], v[114:117]
	v_mfma_f32_16x16x32_bf16 v[106:109], v[164:167], v[216:219], v[106:109]
	v_mfma_f32_16x16x32_bf16 v[98:101], v[172:175], v[216:219], v[98:101]
	v_mfma_f32_16x16x32_bf16 v[88:91], v[164:167], v[224:227], v[88:91]
	v_mfma_f32_16x16x32_bf16 v[80:83], v[172:175], v[224:227], v[80:83]
	v_mfma_f32_16x16x32_bf16 v[72:75], v[164:167], v[232:235], v[72:75]
	v_mfma_f32_16x16x32_bf16 v[64:67], v[172:175], v[232:235], v[64:67]
	v_mfma_f32_16x16x32_bf16 v[122:125], v[168:171], v[184:187], v[122:125]
	v_mfma_f32_16x16x32_bf16 v[114:117], v[176:179], v[184:187], v[114:117]
	v_mfma_f32_16x16x32_bf16 v[106:109], v[168:171], v[220:223], v[106:109]
	v_mfma_f32_16x16x32_bf16 v[98:101], v[176:179], v[220:223], v[98:101]
	v_mfma_f32_16x16x32_bf16 v[88:91], v[168:171], v[228:231], v[88:91]
	v_mfma_f32_16x16x32_bf16 v[80:83], v[176:179], v[228:231], v[80:83]
	v_mfma_f32_16x16x32_bf16 v[72:75], v[168:171], v[236:239], v[72:75]
	v_mfma_f32_16x16x32_bf16 v[64:67], v[176:179], v[236:239], v[64:67]
	s_setprio 0
	s_barrier
	s_add_i32 s36, s54, s8
	v_lshl_add_u64 v[160:161], s[76:77], 0, v[96:97]
	s_mov_b32 m0, s36
	ds_read_b128 v[180:183], v147 offset:16384
	ds_read_b128 v[184:187], v147 offset:17408
	ds_read_b128 v[216:219], v147 offset:18432
	ds_read_b128 v[220:223], v147 offset:19456
	ds_read_b128 v[224:227], v147 offset:20480
	ds_read_b128 v[228:231], v147 offset:21504
	ds_read_b128 v[232:235], v147 offset:22528
	ds_read_b128 v[236:239], v147 offset:23552
	global_load_lds_dwordx4 v[160:161], off
	s_add_i32 m0, s36, 0x2000
	s_add_u32 s36, s76, 0x80000
	v_lshl_add_u64 v[240:241], s[76:77], 0, v[130:131]
	s_addc_u32 s37, s77, 0
	s_add_i32 s54, s55, s8
	global_load_lds_dwordx4 v[240:241], off
	v_lshl_add_u64 v[242:243], s[36:37], 0, v[96:97]
	s_mov_b32 m0, s54
	v_lshl_add_u64 v[244:245], s[78:79], 0, v[132:133]
	global_load_lds_dwordx4 v[242:243], off
	v_lshl_add_u64 v[242:243], s[36:37], 0, v[130:131]
	s_add_i32 m0, s54, 0x2000
	s_nop 0
	global_load_lds_dwordx4 v[242:243], off
	v_lshl_add_u64 v[242:243], s[78:79], 0, v[134:135]
	s_mov_b32 m0, s9
	s_nop 0
	global_load_lds_dwordx4 v[242:243], off
	s_mov_b32 m0, s10
	s_nop 0
	global_load_lds_dwordx4 v[244:245], off
	s_waitcnt vmcnt(8)
	s_waitcnt lgkmcnt(0)
	s_setprio 1
	v_mfma_f32_16x16x32_bf16 v[60:63], v[140:143], v[180:183], v[60:63]
	v_mfma_f32_16x16x32_bf16 v[52:55], v[152:155], v[180:183], v[52:55]
	v_mfma_f32_16x16x32_bf16 v[44:47], v[140:143], v[216:219], v[44:47]
	v_mfma_f32_16x16x32_bf16 v[36:39], v[152:155], v[216:219], v[36:39]
	s_barrier
; #define PG8_STAGE(bufoff, gbase, voff) do { _Pragma("unroll") for (int _i = 0; _i < 2; ++_i) \
;         __builtin_amdgcn_global_load_lds((const unsigned*)((const char*)(gbase) + (voff)[_i]), (LAS unsigned*)(lds + (bufoff) + ldsw + _i * 8192), 16, 0, 0); } while (0)
; #define PG8_LDA(dst, b, h) do { _Pragma("unroll") for (int m = 0; m < 4; ++m) _Pragma("unroll") for (int k = 0; k < 2; ++k) dst[m][k] = *(const LAS bf16x8*)(lds + PG8_SA(b, h) + aoff + m * 2048 + k * 1024); } while (0)
; #define PG8_LDB(dst, b, h) do { _Pragma("unroll") for (int n = 0; n < 2; ++n) _Pragma("unroll") for (int k = 0; k < 2; ++k) dst[n][k] = *(const LAS bf16x8*)(lds + PG8_SB(b, h) + boff + n * 2048 + k * 1024); } while (0)
; #define PG8_MMA(ai, bj, At, Bt) do { __builtin_amdgcn_s_setprio(1); _Pragma("unroll") for (int m = 0; m < 4; ++m) _Pragma("unroll") for (int n = 0; n < 2; ++n) _Pragma("unroll") for (int k = 0; k < 2; ++k) \
;         acc[ai][bj][m][n] = __builtin_amdgcn_mfma_f32_16x16x32_bf16(Bt[n][k], At[m][k], acc[ai][bj][m][n], 0, 0, 0); __builtin_amdgcn_s_setprio(0); } while (0)
; #define PG8_WAIT_V(n) asm volatile("s_waitcnt vmcnt(" #n ")" ::: "memory")
; #define PG8_WAIT_L(n) asm volatile("s_waitcnt lgkmcnt(" #n ")" ::: "memory")
; #define PG8_BAR __builtin_amdgcn_s_barrier()
; #define PG8_SCHED __builtin_amdgcn_sched_barrier(0)
; template <class Epi, bool ALIGN_EPI, bool SP2, bool ROWHALF = false>
; DI void gemm_phase(LAS unsigned char* lds, const Gemm g, const StaticOrder& S, const Epi& E) {
;     ...
;             PG8_WAIT_V(8); PG8_WAIT_L(0); PG8_BAR; if constexpr (!ROWHALF) { PG8_MMA(1, 0, At, B0); PG8_MMA(1, 1, At, B1); } PG8_BAR; PG8_SCHED;
;             PG8_LDB(B0, 1, 0); PG8_LDB(B1, 1, 1); PG8_SCHED; PG8_LDA(At, 1, 0); PG8_STAGE(PG8_SA(0, 1), a2 + hA1, voffA);
;             PG8_WAIT_V(8); PG8_WAIT_L(0); PG8_BAR; PG8_MMA(0, 0, At, B0); PG8_MMA(0, 1, At, B1); PG8_BAR; PG8_SCHED;
	v_mfma_f32_16x16x32_bf16 v[28:31], v[140:143], v[224:227], v[28:31]
	v_mfma_f32_16x16x32_bf16 v[20:23], v[152:155], v[224:227], v[20:23]
	v_mfma_f32_16x16x32_bf16 v[12:15], v[140:143], v[232:235], v[12:15]
	v_mfma_f32_16x16x32_bf16 v[4:7], v[152:155], v[232:235], v[4:7]
	v_mfma_f32_16x16x32_bf16 v[60:63], v[148:151], v[184:187], v[60:63]
	v_mfma_f32_16x16x32_bf16 v[52:55], v[156:159], v[184:187], v[52:55]
	v_mfma_f32_16x16x32_bf16 v[44:47], v[148:151], v[220:223], v[44:47]
	v_mfma_f32_16x16x32_bf16 v[36:39], v[156:159], v[220:223], v[36:39]
	v_mfma_f32_16x16x32_bf16 v[28:31], v[148:151], v[228:231], v[28:31]
	v_mfma_f32_16x16x32_bf16 v[20:23], v[156:159], v[228:231], v[20:23]
	v_mfma_f32_16x16x32_bf16 v[12:15], v[148:151], v[236:239], v[12:15]
	v_mfma_f32_16x16x32_bf16 v[4:7], v[156:159], v[236:239], v[4:7]
	s_setprio 0
	s_setprio 1
	v_mfma_f32_16x16x32_bf16 v[56:59], v[164:167], v[180:183], v[56:59]
	v_mfma_f32_16x16x32_bf16 v[48:51], v[172:175], v[180:183], v[48:51]
	v_mfma_f32_16x16x32_bf16 v[40:43], v[164:167], v[216:219], v[40:43]
	v_mfma_f32_16x16x32_bf16 v[32:35], v[172:175], v[216:219], v[32:35]
	v_mfma_f32_16x16x32_bf16 v[24:27], v[164:167], v[224:227], v[24:27]
	v_mfma_f32_16x16x32_bf16 v[16:19], v[172:175], v[224:227], v[16:19]
	v_mfma_f32_16x16x32_bf16 v[8:11], v[164:167], v[232:235], v[8:11]
	v_mfma_f32_16x16x32_bf16 v[0:3], v[172:175], v[232:235], v[0:3]
	v_mfma_f32_16x16x32_bf16 v[56:59], v[168:171], v[184:187], v[56:59]
	v_mfma_f32_16x16x32_bf16 v[48:51], v[176:179], v[184:187], v[48:51]
	v_mfma_f32_16x16x32_bf16 v[40:43], v[168:171], v[220:223], v[40:43]
	v_mfma_f32_16x16x32_bf16 v[32:35], v[176:179], v[220:223], v[32:35]
	v_mfma_f32_16x16x32_bf16 v[24:27], v[168:171], v[228:231], v[24:27]
	v_mfma_f32_16x16x32_bf16 v[16:19], v[176:179], v[228:231], v[16:19]
	v_mfma_f32_16x16x32_bf16 v[8:11], v[168:171], v[236:239], v[8:11]
	v_mfma_f32_16x16x32_bf16 v[0:3], v[176:179], v[236:239], v[0:3]
	s_setprio 0
	s_barrier
	s_add_i32 s54, 0, 0x18000
	s_add_i32 s55, 0, 0x1c000
	v_add_u32_e32 v156, s54, v145
	v_add_u32_e32 v176, s55, v145
	ds_read_b128 v[140:143], v156
	ds_read_b128 v[148:151], v156 offset:1024
	ds_read_b128 v[152:155], v156 offset:2048
	ds_read_b128 v[156:159], v156 offset:3072
	ds_read_b128 v[164:167], v176
	ds_read_b128 v[168:171], v176 offset:1024
	ds_read_b128 v[172:175], v176 offset:2048
	ds_read_b128 v[176:179], v176 offset:3072
	s_add_u32 s36, s78, 0x80000
	s_addc_u32 s37, s79, 0
	s_mov_b32 m0, s11
	v_lshl_add_u64 v[246:247], s[36:37], 0, v[134:135]
	ds_read_b128 v[180:183], v147 offset:32768
	ds_read_b128 v[184:187], v147 offset:33792
	ds_read_b128 v[216:219], v147 offset:34816
	ds_read_b128 v[220:223], v147 offset:35840
	ds_read_b128 v[224:227], v147 offset:36864
	ds_read_b128 v[228:231], v147 offset:37888
	ds_read_b128 v[232:235], v147 offset:38912
	ds_read_b128 v[236:239], v147 offset:39936
	global_load_lds_dwordx4 v[246:247], off
	v_lshl_add_u64 v[246:247], s[36:37], 0, v[132:133]
	s_mov_b32 m0, s12
	s_nop 0
	global_load_lds_dwordx4 v[246:247], off
	s_waitcnt vmcnt(8)
	s_waitcnt lgkmcnt(0)
	s_setprio 1
	v_mfma_f32_16x16x32_bf16 v[126:129], v[140:143], v[180:183], v[126:129]
	v_mfma_f32_16x16x32_bf16 v[118:121], v[152:155], v[180:183], v[118:121]
	v_mfma_f32_16x16x32_bf16 v[110:113], v[140:143], v[216:219], v[110:113]
	v_mfma_f32_16x16x32_bf16 v[102:105], v[152:155], v[216:219], v[102:105]
	s_barrier
	v_mfma_f32_16x16x32_bf16 v[92:95], v[140:143], v[224:227], v[92:95]
	v_mfma_f32_16x16x32_bf16 v[84:87], v[152:155], v[224:227], v[84:87]
	v_mfma_f32_16x16x32_bf16 v[76:79], v[140:143], v[232:235], v[76:79]
	v_mfma_f32_16x16x32_bf16 v[68:71], v[152:155], v[232:235], v[68:71]
	v_mfma_f32_16x16x32_bf16 v[126:129], v[148:151], v[184:187], v[126:129]
	v_mfma_f32_16x16x32_bf16 v[118:121], v[156:159], v[184:187], v[118:121]
	v_mfma_f32_16x16x32_bf16 v[110:113], v[148:151], v[220:223], v[110:113]
	v_mfma_f32_16x16x32_bf16 v[102:105], v[156:159], v[220:223], v[102:105]
	v_mfma_f32_16x16x32_bf16 v[92:95], v[148:151], v[228:231], v[92:95]
	v_mfma_f32_16x16x32_bf16 v[84:87], v[156:159], v[228:231], v[84:87]
	v_mfma_f32_16x16x32_bf16 v[76:79], v[148:151], v[236:239], v[76:79]
	v_mfma_f32_16x16x32_bf16 v[68:71], v[156:159], v[236:239], v[68:71]
	s_setprio 0
	s_setprio 1
	v_mfma_f32_16x16x32_bf16 v[122:125], v[164:167], v[180:183], v[122:125]
	v_mfma_f32_16x16x32_bf16 v[114:117], v[172:175], v[180:183], v[114:117]
	v_mfma_f32_16x16x32_bf16 v[106:109], v[164:167], v[216:219], v[106:109]
	v_mfma_f32_16x16x32_bf16 v[98:101], v[172:175], v[216:219], v[98:101]
	v_mfma_f32_16x16x32_bf16 v[88:91], v[164:167], v[224:227], v[88:91]
	v_mfma_f32_16x16x32_bf16 v[80:83], v[172:175], v[224:227], v[80:83]
	v_mfma_f32_16x16x32_bf16 v[72:75], v[164:167], v[232:235], v[72:75]
	v_mfma_f32_16x16x32_bf16 v[64:67], v[172:175], v[232:235], v[64:67]
	v_mfma_f32_16x16x32_bf16 v[122:125], v[168:171], v[184:187], v[122:125]
	v_mfma_f32_16x16x32_bf16 v[114:117], v[176:179], v[184:187], v[114:117]
	v_mfma_f32_16x16x32_bf16 v[106:109], v[168:171], v[220:223], v[106:109]
	v_mfma_f32_16x16x32_bf16 v[98:101], v[176:179], v[220:223], v[98:101]
	v_mfma_f32_16x16x32_bf16 v[88:91], v[168:171], v[228:231], v[88:91]
	v_mfma_f32_16x16x32_bf16 v[80:83], v[176:179], v[228:231], v[80:83]
	v_mfma_f32_16x16x32_bf16 v[72:75], v[168:171], v[236:239], v[72:75]
	v_mfma_f32_16x16x32_bf16 v[64:67], v[176:179], v[236:239], v[64:67]
	s_setprio 0
	s_barrier
; #define PG8_STAGE(bufoff, gbase, voff) do { _Pragma("unroll") for (int _i = 0; _i < 2; ++_i) \
;         __builtin_amdgcn_global_load_lds((const unsigned*)((const char*)(gbase) + (voff)[_i]), (LAS unsigned*)(lds + (bufoff) + ldsw + _i * 8192), 16, 0, 0); } while (0)
; #define PG8_LDA(dst, b, h) do { _Pragma("unroll") for (int m = 0; m < 4; ++m) _Pragma("unroll") for (int k = 0; k < 2; ++k) dst[m][k] = *(const LAS bf16x8*)(lds + PG8_SA(b, h) + aoff + m * 2048 + k * 1024); } while (0)
; #define PG8_MMA(ai, bj, At, Bt) do { __builtin_amdgcn_s_setprio(1); _Pragma("unroll") for (int m = 0; m < 4; ++m) _Pragma("unroll") for (int n = 0; n < 2; ++n) _Pragma("unroll") for (int k = 0; k < 2; ++k) \
;         acc[ai][bj][m][n] = __builtin_amdgcn_mfma_f32_16x16x32_bf16(Bt[n][k], At[m][k], acc[ai][bj][m][n], 0, 0, 0); __builtin_amdgcn_s_setprio(0); } while (0)
; #define PG8_WAIT_V(n) asm volatile("s_waitcnt vmcnt(" #n ")" ::: "memory")
; #define PG8_WAIT_L(n) asm volatile("s_waitcnt lgkmcnt(" #n ")" ::: "memory")
; #define PG8_BAR __builtin_amdgcn_s_barrier()
; #define PG8_SCHED __builtin_amdgcn_sched_barrier(0)
; template <class Epi, bool ALIGN_EPI, bool SP2, bool ROWHALF = false>
; DI void gemm_phase(LAS unsigned char* lds, const Gemm g, const StaticOrder& S, const Epi& E) {
;     ...
;         for (int t = 0; t < nt; t += 2) {
;             const bool last = (t == nt - 2);
;             const char* a1 = cA + (size_t)(t + 1) * kstep;
;             const char* a2 = last ? nA : cA + (size_t)(t + 2) * kstep; const char* b2 = last ? nB : cB + (size_t)(t + 2) * kstep;
;             const char* a3 = a2 + kstep; const char* b3 = b2 + kstep;
;     ...
;             if constexpr (!ROWHALF) { PG8_LDA(At, 1, 1); } PG8_STAGE(PG8_SB(1, 0), b3, voffB); PG8_STAGE(PG8_SB(1, 1), b3 + hstepB, voffB); PG8_STAGE(PG8_SA(1, 0), a3 + hA0, voffA);
;             PG8_WAIT_V(8); PG8_WAIT_L(0); PG8_BAR; if constexpr (!ROWHALF) { PG8_MMA(1, 0, At, B0); PG8_MMA(1, 1, At, B1); } PG8_BAR; PG8_SCHED;
	s_add_i32 s36, s54, s8
	v_lshl_add_u64 v[160:161], v[160:161], 0, s[38:39]
	s_mov_b32 m0, s36
	ds_read_b128 v[180:183], v147 offset:49152
	ds_read_b128 v[184:187], v147 offset:50176
	ds_read_b128 v[216:219], v147 offset:51200
	ds_read_b128 v[220:223], v147 offset:52224
	ds_read_b128 v[224:227], v147 offset:53248
	ds_read_b128 v[228:231], v147 offset:54272
	ds_read_b128 v[232:235], v147 offset:55296
	ds_read_b128 v[236:239], v147 offset:56320
	global_load_lds_dwordx4 v[160:161], off
	s_add_i32 m0, s36, 0x2000
	s_add_u32 s36, s76, 0x80080
	v_lshl_add_u64 v[160:161], v[240:241], 0, s[38:39]
	s_addc_u32 s37, s77, 0
	s_add_i32 s54, s55, s8
	global_load_lds_dwordx4 v[160:161], off
	v_lshl_add_u64 v[160:161], s[36:37], 0, v[96:97]
	s_mov_b32 m0, s54
	s_nop 0
	global_load_lds_dwordx4 v[160:161], off
	v_lshl_add_u64 v[160:161], s[36:37], 0, v[130:131]
	s_add_i32 m0, s54, 0x2000
	s_nop 0
	global_load_lds_dwordx4 v[160:161], off
	v_lshl_add_u64 v[160:161], v[242:243], 0, s[38:39]
	s_mov_b32 m0, s31
	s_nop 0
	global_load_lds_dwordx4 v[160:161], off
	v_lshl_add_u64 v[160:161], v[244:245], 0, s[38:39]
	s_mov_b32 m0, s46
	s_nop 0
	global_load_lds_dwordx4 v[160:161], off
	s_waitcnt vmcnt(8)
	s_waitcnt lgkmcnt(0)
	s_setprio 1
	v_mfma_f32_16x16x32_bf16 v[60:63], v[140:143], v[180:183], v[60:63]
	v_mfma_f32_16x16x32_bf16 v[52:55], v[152:155], v[180:183], v[52:55]
	v_mfma_f32_16x16x32_bf16 v[44:47], v[140:143], v[216:219], v[44:47]
	v_mfma_f32_16x16x32_bf16 v[36:39], v[152:155], v[216:219], v[36:39]
	s_barrier
	v_mfma_f32_16x16x32_bf16 v[28:31], v[140:143], v[224:227], v[28:31]
	v_mfma_f32_16x16x32_bf16 v[20:23], v[152:155], v[224:227], v[20:23]
	v_mfma_f32_16x16x32_bf16 v[12:15], v[140:143], v[232:235], v[12:15]
	v_mfma_f32_16x16x32_bf16 v[4:7], v[152:155], v[232:235], v[4:7]
	v_mfma_f32_16x16x32_bf16 v[60:63], v[148:151], v[184:187], v[60:63]
	v_mfma_f32_16x16x32_bf16 v[52:55], v[156:159], v[184:187], v[52:55]
	v_mfma_f32_16x16x32_bf16 v[44:47], v[148:151], v[220:223], v[44:47]
	v_mfma_f32_16x16x32_bf16 v[36:39], v[156:159], v[220:223], v[36:39]
	v_mfma_f32_16x16x32_bf16 v[28:31], v[148:151], v[228:231], v[28:31]
	v_mfma_f32_16x16x32_bf16 v[20:23], v[156:159], v[228:231], v[20:23]
	v_mfma_f32_16x16x32_bf16 v[12:15], v[148:151], v[236:239], v[12:15]
	v_mfma_f32_16x16x32_bf16 v[4:7], v[156:159], v[236:239], v[4:7]
	s_setprio 0
	s_setprio 1
	v_mfma_f32_16x16x32_bf16 v[56:59], v[164:167], v[180:183], v[56:59]
	s_add_i32 s53, s53, 2
	v_mfma_f32_16x16x32_bf16 v[48:51], v[172:175], v[180:183], v[48:51]
	s_add_u32 s74, s74, 0x100
	s_addc_u32 s75, s75, 0
	v_mfma_f32_16x16x32_bf16 v[40:43], v[164:167], v[216:219], v[40:43]
	s_add_u32 s47, s47, 0x100
	s_addc_u32 s51, s51, 0
	v_mfma_f32_16x16x32_bf16 v[32:35], v[172:175], v[216:219], v[32:35]
	s_add_u32 s36, s74, 0xfff80080
	s_addc_u32 s37, s75, -1
	v_mfma_f32_16x16x32_bf16 v[24:27], v[164:167], v[224:227], v[24:27]
	s_add_i32 s54, 0, 0x10000
	v_mfma_f32_16x16x32_bf16 v[16:19], v[172:175], v[224:227], v[16:19]
	s_cmp_eq_u32 s53, 28
	s_cselect_b32 s79, s20, s37
	v_mfma_f32_16x16x32_bf16 v[8:11], v[164:167], v[232:235], v[8:11]
	s_cselect_b32 s78, s21, s36
	s_cselect_b32 s77, s29, s51
	v_mfma_f32_16x16x32_bf16 v[0:3], v[172:175], v[232:235], v[0:3]
	s_cselect_b32 s76, s43, s47
	s_add_i32 s55, 0, 0x14000
	v_mfma_f32_16x16x32_bf16 v[56:59], v[168:171], v[184:187], v[56:59]
	v_mfma_f32_16x16x32_bf16 v[48:51], v[176:179], v[184:187], v[48:51]
	v_mfma_f32_16x16x32_bf16 v[40:43], v[168:171], v[220:223], v[40:43]
	v_mfma_f32_16x16x32_bf16 v[32:35], v[176:179], v[220:223], v[32:35]
	v_mfma_f32_16x16x32_bf16 v[24:27], v[168:171], v[228:231], v[24:27]
	v_mfma_f32_16x16x32_bf16 v[16:19], v[176:179], v[228:231], v[16:19]
	v_mfma_f32_16x16x32_bf16 v[8:11], v[168:171], v[236:239], v[8:11]
	v_mfma_f32_16x16x32_bf16 v[0:3], v[176:179], v[236:239], v[0:3]
	s_setprio 0
	s_cmp_gt_u32 s53, 29
	s_barrier
	s_cbranch_scc0 .Lk240_body
	s_and_b64 vcc, exec, s[24:25]
	s_cbranch_vccz .LBB0_243
	s_barrier
